# cost-weighted VALU spacing: attention finishSM interleave packed 8 issue-slots per qkt MFMA gap (was 6), leaving the last MFMAs bare
# speedup vs baseline: 1.0034x; 1.0034x over previous
; #define LAS __attribute__((address_space(3)))
; __device__ __forceinline__ void finishSM(f32x16& p0, f32x16& p1, float alpha, float& l_reg, bf16x8& pa0, bf16x8& pa1, bf16x8& pa2, bf16x8& pa3) {
; #pragma unroll
;     for (int r = 0; r < 16; ++r) p1[r] = __builtin_amdgcn_exp2f(p1[r]);
;     float ps = 0;
; #pragma unroll
;     for (int r = 0; r < 16; ++r) ps += p0[r];
; #pragma unroll
;     for (int r = 0; r < 16; ++r) ps += p1[r];
;     { auto rr = __builtin_amdgcn_permlane32_swap(__float_as_uint(ps), __float_as_uint(ps), false, false);
;       ps = __uint_as_float(rr[0]) + __uint_as_float(rr[1]); }
;     l_reg = l_reg * alpha + ps;
;     ...
;     PK4(p0, 0, pa0); PK4(p0, 8, pa1); PK4(p1, 0, pa2); PK4(p1, 8, pa3);
;     ...
; }
; template <int KB>
; __device__ __forceinline__ void qkt(f32x16& p0, f32x16& p1, lptr K_lds, int r32, int hi, const bf16x8* qr) {
;     p0 = f32x16{}; p1 = f32x16{};
;     lptr kb[4];
; #pragma unroll
;     for (int dd = 0; dd < 4; ++dd) kb[dd] = K_lds + KB * SHM_K + KSWZ(r32, (dd * 16 + hi * 8) * 2);
; #pragma unroll
;     for (int d0 = 0; d0 < 8; ++d0) { lptr a = kb[d0 & 3] + (d0 >> 2) * 128;
;         bf16x8 b0 = *reinterpret_cast<const LAS bf16x8*>(a);
;         bf16x8 b1 = *reinterpret_cast<const LAS bf16x8*>(a + 32 * 256);
;         p0 = __builtin_amdgcn_mfma_f32_32x32x16_bf16(b0, qr[d0], p0, 0, 0, 0);
;         p1 = __builtin_amdgcn_mfma_f32_32x32x16_bf16(b1, qr[d0], p1, 0, 0, 0); }
; }
.LBB0_865:
	ds_read_b128 v[82:85], v187 offset:49152
	ds_read_b128 v[86:89], v187 offset:57344
	ds_read_b128 v[236:239], v185 offset:49152
	ds_read_b128 v[240:243], v185 offset:57344
	s_waitcnt lgkmcnt(3)
	v_mfma_f32_32x32x16_bf16 v[98:113], v[82:85], v[142:145], 0
	v_exp_f32_e32 v80, v80
	v_exp_f32_e32 v1, v1
	v_exp_f32_e32 v78, v78
	v_exp_f32_e32 v79, v79
	s_waitcnt lgkmcnt(2)
	v_mfma_f32_32x32x16_bf16 v[82:97], v[86:89], v[142:145], 0
	v_exp_f32_e32 v76, v76
	v_exp_f32_e32 v77, v77
	v_exp_f32_e32 v81, v74
	v_exp_f32_e32 v146, v75
	s_waitcnt lgkmcnt(0)
	v_mfma_f32_32x32x16_bf16 v[82:97], v[240:243], v[138:141], v[82:97]
	v_exp_f32_e32 v226, v72
	v_exp_f32_e32 v233, v66
	v_add_f32_e32 v66, 0, v160
	v_add_f32_e32 v66, v227, v66
	v_add_f32_e32 v66, v158, v66
	v_add_f32_e32 v66, v161, v66
	v_mfma_f32_32x32x16_bf16 v[98:113], v[236:239], v[138:141], v[98:113]
	v_add_f32_e32 v66, v157, v66
	v_add_f32_e32 v66, v159, v66
	v_add_f32_e32 v66, v155, v66
	v_add_f32_e32 v66, v156, v66
	v_add_f32_e32 v66, v152, v66
	v_add_f32_e32 v66, v154, v66
	v_add_f32_e32 v66, v151, v66
	v_add_f32_e32 v66, v153, v66
	ds_read_b128 v[236:239], v184 offset:49152
	ds_read_b128 v[240:243], v184 offset:57344
	s_waitcnt lgkmcnt(0)
	v_mfma_f32_32x32x16_bf16 v[82:97], v[240:243], v[134:137], v[82:97]
	v_add_f32_e32 v66, v148, v66
	v_add_f32_e32 v66, v150, v66
	v_add_f32_e32 v66, v147, v66
	v_add_f32_e32 v66, v149, v66
	v_add_f32_e32 v66, v80, v66
	v_add_f32_e32 v66, v1, v66
	v_add_f32_e32 v66, v78, v66
	v_add_f32_e32 v66, v79, v66
	v_mfma_f32_32x32x16_bf16 v[98:113], v[236:239], v[134:137], v[98:113]
	v_add_f32_e32 v66, v76, v66
	v_exp_f32_e32 v228, v73
	v_add_f32_e32 v66, v77, v66
	v_exp_f32_e32 v229, v70
	v_add_f32_e32 v66, v81, v66
	ds_read_b128 v[236:239], v183 offset:49152
	ds_read_b128 v[240:243], v183 offset:57344
	s_waitcnt lgkmcnt(0)
	v_mfma_f32_32x32x16_bf16 v[82:97], v[240:243], v[130:133], v[82:97]
	v_exp_f32_e32 v230, v71
	v_add_f32_e32 v66, v146, v66
	v_exp_f32_e32 v231, v68
	v_add_f32_e32 v66, v226, v66
	v_exp_f32_e32 v232, v69
	v_mfma_f32_32x32x16_bf16 v[98:113], v[236:239], v[130:133], v[98:113]
	v_add_f32_e32 v66, v228, v66
	v_add_f32_e32 v66, v229, v66
	v_exp_f32_e32 v234, v67
	v_add_f32_e32 v66, v230, v66
	v_add_f32_e32 v66, v231, v66
	v_add_f32_e32 v66, v232, v66
	v_add_f32_e32 v66, v233, v66
	ds_read_b128 v[236:239], v187 offset:49280
	ds_read_b128 v[240:243], v187 offset:57472
	s_waitcnt lgkmcnt(0)
	v_mfma_f32_32x32x16_bf16 v[82:97], v[240:243], v[126:129], v[82:97]
	v_add_f32_e32 v224, v234, v66
	v_mov_b32_e32 v225, v224
	v_cvt_pk_bf16_f32 v66, v160, v227
	v_cvt_pk_bf16_f32 v67, v158, v161
	v_cvt_pk_bf16_f32 v68, v157, v159
	v_cvt_pk_bf16_f32 v69, v155, v156
	v_cvt_pk_bf16_f32 v70, v152, v154
	v_cvt_pk_bf16_f32 v71, v151, v153
	v_mfma_f32_32x32x16_bf16 v[98:113], v[236:239], v[126:129], v[98:113]
	v_cvt_pk_bf16_f32 v72, v148, v150
	v_cvt_pk_bf16_f32 v73, v147, v149
	v_cvt_pk_bf16_f32 v74, v80, v1
	v_cvt_pk_bf16_f32 v75, v78, v79
	v_cvt_pk_bf16_f32 v76, v76, v77
	v_cvt_pk_bf16_f32 v77, v81, v146
	v_cvt_pk_bf16_f32 v78, v226, v228
	v_cvt_pk_bf16_f32 v79, v229, v230
	ds_read_b128 v[236:239], v185 offset:49280
	ds_read_b128 v[240:243], v185 offset:57472
	s_waitcnt lgkmcnt(0)
	v_mfma_f32_32x32x16_bf16 v[82:97], v[240:243], v[122:125], v[82:97]
	v_cvt_pk_bf16_f32 v80, v231, v232
	v_cvt_pk_bf16_f32 v81, v233, v234
	s_nop 1
	v_permlane32_swap_b32_e32 v224, v225
	v_permlane32_swap_b32_e32 v66, v68
	v_permlane32_swap_b32_e32 v67, v69
	v_permlane32_swap_b32_e32 v70, v72
	v_permlane32_swap_b32_e32 v71, v73
	v_mfma_f32_32x32x16_bf16 v[98:113], v[236:239], v[122:125], v[98:113]
	v_permlane32_swap_b32_e32 v74, v76
	v_permlane32_swap_b32_e32 v75, v77
	v_permlane32_swap_b32_e32 v78, v80
	v_permlane32_swap_b32_e32 v79, v81
	ds_read_b128 v[236:239], v184 offset:49280
	ds_read_b128 v[240:243], v184 offset:57472
	s_waitcnt lgkmcnt(0)
	v_mfma_f32_32x32x16_bf16 v[82:97], v[240:243], v[118:121], v[82:97]
	v_mfma_f32_32x32x16_bf16 v[98:113], v[236:239], v[118:121], v[98:113]
	ds_read_b128 v[236:239], v183 offset:49280
	ds_read_b128 v[240:243], v183 offset:57472
	s_waitcnt lgkmcnt(0)
	v_mfma_f32_32x32x16_bf16 v[82:97], v[240:243], v[114:117], v[82:97]
	v_mfma_f32_32x32x16_bf16 v[98:113], v[236:239], v[114:117], v[98:113]
	v_add_u32_e32 v227, s89, v186
	v_add_u32_e32 v146, 1, v227
	v_add_u32_e32 v148, 33, v227
	v_ashrrev_i32_e32 v147, 31, v146
	v_ashrrev_i32_e32 v149, 31, v148
	v_lshlrev_b64 v[154:155], 8, v[146:147]
	v_lshlrev_b64 v[156:157], 8, v[148:149]
	v_lshl_add_u64 v[146:147], v[176:177], 0, v[154:155]
	v_lshl_add_u64 v[150:151], v[176:177], 0, v[156:157]
	v_lshl_add_u64 v[154:155], v[178:179], 0, v[154:155]
	v_lshl_add_u64 v[158:159], v[178:179], 0, v[156:157]
	global_load_dwordx4 v[146:149], v[146:147], off
	s_nop 0
	global_load_dwordx4 v[150:153], v[150:151], off
	s_nop 0
	global_load_dwordx4 v[154:157], v[154:155], off
	s_nop 0
	global_load_dwordx4 v[158:161], v[158:159], off
	ds_read_b64_tr_b16 v[228:229], v181 offset:0
	ds_read_b64_tr_b16 v[230:231], v181 offset:0x800
	ds_read_b64_tr_b16 v[232:233], v181 offset:0x1000
	ds_read_b64_tr_b16 v[234:235], v181 offset:0x1800
	ds_read_b64_tr_b16 v[236:237], v181 offset:0x2000
	ds_read_b64_tr_b16 v[238:239], v181 offset:0x2800
	ds_read_b64_tr_b16 v[240:241], v181 offset:0x3000
	ds_read_b64_tr_b16 v[242:243], v181 offset:0x3800
	s_waitcnt lgkmcnt(0)
; #define LAS __attribute__((address_space(3)))
; __device__ __forceinline__ void bias_tile(f32x16& p0, f32x16& p1, const LAS float* cs) {
; #pragma unroll
;     for (int i = 0; i < 4; ++i) { const f32x4 a = *(const LAS f32x4*)(cs + 8 * i), b = *(const LAS f32x4*)(cs + 32 + 8 * i);
; #pragma unroll
;         for (int j = 0; j < 4; ++j) { p0[4 * i + j] = fmaf(p0[4 * i + j], C2, a[j]); p1[4 * i + j] = fmaf(p1[4 * i + j], C2, b[j]); } }
; }
; template <int VB>
; __device__ __forceinline__ void pv_tile(f32x16* o, int vb0, bf16x8 pa0, bf16x8 pa1, bf16x8 pa2, bf16x8 pa3) {
;     ...
;     PV_D0(0); PV_D0(1); PV_D0(2); PV_D0(3);
	s_nop 0
	v_mfma_f32_32x32x16_bf16 v[50:65], v[66:69], v[228:231], v[50:65]
	ds_read_b64_tr_b16 v[228:229], v181 offset:0x200
	ds_read_b64_tr_b16 v[230:231], v181 offset:0xa00
	v_mfma_f32_32x32x16_bf16 v[50:65], v[70:73], v[232:235], v[50:65]
	ds_read_b64_tr_b16 v[232:233], v181 offset:0x1200
	ds_read_b64_tr_b16 v[234:235], v181 offset:0x1a00
	v_mfma_f32_32x32x16_bf16 v[50:65], v[74:77], v[236:239], v[50:65]
	ds_read_b64_tr_b16 v[236:237], v181 offset:0x2200
	ds_read_b64_tr_b16 v[238:239], v181 offset:0x2a00
	v_mfma_f32_32x32x16_bf16 v[50:65], v[78:81], v[240:243], v[50:65]
	ds_read_b64_tr_b16 v[240:241], v181 offset:0x3200
	ds_read_b64_tr_b16 v[242:243], v181 offset:0x3a00
	s_waitcnt lgkmcnt(0)
	v_mfma_f32_32x32x16_bf16 v[34:49], v[66:69], v[228:231], v[34:49]
	ds_read_b64_tr_b16 v[228:229], v181 offset:0x400
	ds_read_b64_tr_b16 v[230:231], v181 offset:0xc00
	v_mfma_f32_32x32x16_bf16 v[34:49], v[70:73], v[232:235], v[34:49]
	ds_read_b64_tr_b16 v[232:233], v181 offset:0x1400
	ds_read_b64_tr_b16 v[234:235], v181 offset:0x1c00
	v_mfma_f32_32x32x16_bf16 v[34:49], v[74:77], v[236:239], v[34:49]
	ds_read_b64_tr_b16 v[236:237], v181 offset:0x2400
	ds_read_b64_tr_b16 v[238:239], v181 offset:0x2c00
	v_mfma_f32_32x32x16_bf16 v[34:49], v[78:81], v[240:243], v[34:49]
	ds_read_b64_tr_b16 v[240:241], v181 offset:0x3400
	ds_read_b64_tr_b16 v[242:243], v181 offset:0x3c00
	s_waitcnt lgkmcnt(0)
	v_mfma_f32_32x32x16_bf16 v[18:33], v[66:69], v[228:231], v[18:33]
	ds_read_b64_tr_b16 v[228:229], v181 offset:0x600
	ds_read_b64_tr_b16 v[230:231], v181 offset:0xe00
	v_mfma_f32_32x32x16_bf16 v[18:33], v[70:73], v[232:235], v[18:33]
	ds_read_b64_tr_b16 v[232:233], v181 offset:0x1600
	ds_read_b64_tr_b16 v[234:235], v181 offset:0x1e00
	v_mfma_f32_32x32x16_bf16 v[18:33], v[74:77], v[236:239], v[18:33]
	ds_read_b64_tr_b16 v[236:237], v181 offset:0x2600
	ds_read_b64_tr_b16 v[238:239], v181 offset:0x2e00
	v_mfma_f32_32x32x16_bf16 v[18:33], v[78:81], v[240:243], v[18:33]
	ds_read_b64_tr_b16 v[240:241], v181 offset:0x3600
	ds_read_b64_tr_b16 v[242:243], v181 offset:0x3e00
	s_waitcnt lgkmcnt(0)
	v_mfma_f32_32x32x16_bf16 v[2:17], v[66:69], v[228:231], v[2:17]
	s_cmp_le_i32 s89, s80
	v_mfma_f32_32x32x16_bf16 v[2:17], v[70:73], v[232:235], v[2:17]
	v_mfma_f32_32x32x16_bf16 v[2:17], v[74:77], v[236:239], v[2:17]
	v_mfma_f32_32x32x16_bf16 v[2:17], v[78:81], v[240:243], v[2:17]
	ds_read_b128 v[228:231], v223 offset:128
	ds_read_b128 v[78:81], v223
	ds_read_b128 v[70:73], v223 offset:32
	ds_read_b128 v[232:235], v223 offset:160
	ds_read_b128 v[74:77], v223 offset:64
	ds_read_b128 v[236:239], v223 offset:192
	ds_read_b128 v[240:243], v223 offset:96
	ds_read_b128 v[244:247], v223 offset:224
	s_waitcnt lgkmcnt(6)
	v_pk_fma_f32 v[100:101], v[100:101], s[2:3], v[80:81] op_sel_hi:[1,0,1]
	s_waitcnt lgkmcnt(3)
	v_pk_fma_f32 v[68:69], v[106:107], s[2:3], v[74:75] op_sel_hi:[1,0,1]
	v_pk_fma_f32 v[74:75], v[102:103], s[2:3], v[70:71] op_sel_hi:[1,0,1]
	s_waitcnt lgkmcnt(1)
	v_pk_fma_f32 v[66:67], v[110:111], s[2:3], v[240:241] op_sel_hi:[1,0,1]
	v_pk_fma_f32 v[70:71], v[112:113], s[2:3], v[242:243] op_sel_hi:[1,0,1]
	v_pk_fma_f32 v[76:77], v[108:109], s[2:3], v[76:77] op_sel_hi:[1,0,1]
	v_pk_fma_f32 v[102:103], v[104:105], s[2:3], v[72:73] op_sel_hi:[1,0,1]
	v_pk_fma_f32 v[98:99], v[98:99], s[2:3], v[78:79] op_sel_hi:[1,0,1]
	s_waitcnt lgkmcnt(0)
	v_pk_fma_f32 v[72:73], v[94:95], s[2:3], v[244:245] op_sel_hi:[1,0,1]
	v_pk_fma_f32 v[78:79], v[90:91], s[2:3], v[236:237] op_sel_hi:[1,0,1]
	v_pk_fma_f32 v[86:87], v[86:87], s[2:3], v[232:233] op_sel_hi:[1,0,1]
	v_pk_fma_f32 v[80:81], v[96:97], s[2:3], v[246:247] op_sel_hi:[1,0,1]
	v_pk_fma_f32 v[90:91], v[92:93], s[2:3], v[238:239] op_sel_hi:[1,0,1]
	v_pk_fma_f32 v[88:89], v[88:89], s[2:3], v[234:235] op_sel_hi:[1,0,1]
	v_pk_fma_f32 v[84:85], v[84:85], s[2:3], v[230:231] op_sel_hi:[1,0,1]
	v_pk_fma_f32 v[82:83], v[82:83], s[2:3], v[228:229] op_sel_hi:[1,0,1]
	s_cbranch_scc1 .LBB0_867
; __device__ __forceinline__ void mask_tile(f32x16& p0, f32x16& p1, int dq) {
;     const float NEG = -__builtin_inff();
; #pragma unroll
;     for (int r = 0; r < 16; ++r) { const int c = (r & 3) + 8 * (r >> 2);
;         if (dq - c < 0) p0[r] = NEG;
;         if (dq - c - 32 < 0) p1[r] = NEG; }
; }
	v_add_u32_e32 v1, 64, v222
	v_cmp_gt_i32_e64 s[70:71], 26, v1
	v_cmp_gt_i32_e64 s[72:73], 27, v1
	v_cmp_gt_i32_e64 s[68:69], 25, v1
	s_and_b64 s[70:71], s[72:73], s[70:71]
	v_cmp_gt_i32_e64 s[66:67], 24, v1
	s_and_b64 s[68:69], s[70:71], s[68:69]
	v_cmp_gt_i32_e64 s[64:65], 19, v1
	s_and_b64 s[66:67], s[68:69], s[66:67]
	v_cmp_gt_i32_e64 s[62:63], 18, v1
	s_and_b64 s[64:65], s[66:67], s[64:65]
	v_cmp_gt_i32_e64 s[60:61], 17, v1
	s_and_b64 s[62:63], s[64:65], s[62:63]
	v_cmp_gt_i32_e64 s[58:59], 16, v1
	s_and_b64 s[60:61], s[62:63], s[60:61]
	v_cmp_gt_i32_e64 s[56:57], 11, v1
	s_and_b64 s[58:59], s[60:61], s[58:59]
	v_cmp_gt_i32_e64 s[54:55], 10, v1
	s_and_b64 s[56:57], s[58:59], s[56:57]
	v_cmp_gt_i32_e64 s[52:53], 9, v1
	s_and_b64 s[54:55], s[56:57], s[54:55]
	v_cmp_gt_i32_e64 s[50:51], 8, v1
	s_and_b64 s[52:53], s[54:55], s[52:53]
	v_cmp_gt_i32_e64 s[48:49], 3, v1
	s_and_b64 s[50:51], s[52:53], s[50:51]
	v_cmp_gt_i32_e64 s[46:47], 2, v1
	s_and_b64 s[48:49], s[50:51], s[48:49]
	v_cmp_gt_i32_e64 s[44:45], 1, v1
	s_and_b64 s[46:47], s[48:49], s[46:47]
	v_cmp_gt_i32_e64 s[42:43], 0, v1
	s_and_b64 s[44:45], s[46:47], s[44:45]
	s_and_b64 s[42:43], s[44:45], s[42:43]
	v_cmp_gt_i32_e64 s[38:39], 58, v1
	v_cndmask_b32_e64 v98, v98, v206, s[42:43]
	v_cmp_gt_i32_e64 s[42:43], 59, v1
	v_cmp_gt_i32_e64 s[36:37], 57, v1
	s_and_b64 s[38:39], s[42:43], s[38:39]
	v_cmp_gt_i32_e64 s[34:35], 56, v1
	s_and_b64 s[36:37], s[38:39], s[36:37]
	v_cmp_gt_i32_e64 s[30:31], 51, v1
	s_and_b64 s[34:35], s[36:37], s[34:35]
	v_cmp_gt_i32_e64 s[28:29], 50, v1
	s_and_b64 s[30:31], s[34:35], s[30:31]
	v_cmp_gt_i32_e64 s[26:27], 49, v1
	s_and_b64 s[28:29], s[30:31], s[28:29]
	v_cmp_gt_i32_e64 s[24:25], 48, v1
	s_and_b64 s[26:27], s[28:29], s[26:27]
	v_cmp_gt_i32_e64 s[22:23], 43, v1
	s_and_b64 s[24:25], s[26:27], s[24:25]
	v_cmp_gt_i32_e64 s[20:21], 42, v1
	s_and_b64 s[22:23], s[24:25], s[22:23]
	v_cmp_gt_i32_e64 s[18:19], 41, v1
	s_and_b64 s[20:21], s[22:23], s[20:21]
	v_cmp_gt_i32_e64 s[16:17], 40, v1
	s_and_b64 s[18:19], s[20:21], s[18:19]
	v_cmp_gt_i32_e64 s[14:15], 35, v1
	s_and_b64 s[16:17], s[18:19], s[16:17]
	v_cmp_gt_i32_e64 s[12:13], 34, v1
	s_and_b64 s[14:15], s[16:17], s[14:15]
	v_cmp_gt_i32_e64 s[10:11], 33, v1
	s_and_b64 s[12:13], s[14:15], s[12:13]
	v_cmp_gt_i32_e32 vcc, 32, v1
	s_and_b64 s[10:11], s[12:13], s[10:11]
	s_and_b64 vcc, s[10:11], vcc
	v_cndmask_b32_e64 v71, v71, v206, s[72:73]
	v_cndmask_b32_e64 v70, v70, v206, s[70:71]
	v_cndmask_b32_e64 v67, v67, v206, s[68:69]
	v_cndmask_b32_e64 v66, v66, v206, s[66:67]
	v_cndmask_b32_e64 v77, v77, v206, s[64:65]
	v_cndmask_b32_e64 v76, v76, v206, s[62:63]
	v_cndmask_b32_e64 v69, v69, v206, s[60:61]
	v_cndmask_b32_e64 v68, v68, v206, s[58:59]
	v_cndmask_b32_e64 v103, v103, v206, s[56:57]
	v_cndmask_b32_e64 v102, v102, v206, s[54:55]
	v_cndmask_b32_e64 v75, v75, v206, s[52:53]
	v_cndmask_b32_e64 v74, v74, v206, s[50:51]
	v_cndmask_b32_e64 v101, v101, v206, s[48:49]
	v_cndmask_b32_e64 v100, v100, v206, s[46:47]
	v_cndmask_b32_e64 v99, v99, v206, s[44:45]
	v_cndmask_b32_e64 v81, v81, v206, s[42:43]
	v_cndmask_b32_e64 v80, v80, v206, s[38:39]
	v_cndmask_b32_e64 v73, v73, v206, s[36:37]
	v_cndmask_b32_e64 v72, v72, v206, s[34:35]
	v_cndmask_b32_e64 v91, v91, v206, s[30:31]
	v_cndmask_b32_e64 v90, v90, v206, s[28:29]
	v_cndmask_b32_e64 v79, v79, v206, s[26:27]
	v_cndmask_b32_e64 v78, v78, v206, s[24:25]
	v_cndmask_b32_e64 v89, v89, v206, s[22:23]
	v_cndmask_b32_e64 v88, v88, v206, s[20:21]
	v_cndmask_b32_e64 v87, v87, v206, s[18:19]
	v_cndmask_b32_e64 v86, v86, v206, s[16:17]
	v_cndmask_b32_e64 v85, v85, v206, s[14:15]
	v_cndmask_b32_e64 v84, v84, v206, s[12:13]
	v_cndmask_b32_e64 v83, v83, v206, s[10:11]
	v_cndmask_b32_e32 v82, v82, v206, vcc

; #define LAS __attribute__((address_space(3)))
; __device__ __forceinline__ void partialSM(f32x16& p0, f32x16& p1, float& m_reg, float& alpha) {
;     float pmax = p0[0];
; #pragma unroll
;     for (int r = 1; r < 16; ++r) pmax = fmaxf(pmax, p0[r]);
; #pragma unroll
;     for (int r = 0; r < 16; ++r) pmax = fmaxf(pmax, p1[r]);
;     { auto rr = __builtin_amdgcn_permlane32_swap(__float_as_uint(pmax), __float_as_uint(pmax), false, false);
;       pmax = fmaxf(__uint_as_float(rr[0]), __uint_as_float(rr[1])); }
;     float mn;
;     if (__builtin_expect(__all(pmax - m_reg <= THR2), 1)) { mn = m_reg; alpha = 1.f; }
;     else { mn = fmaxf(m_reg, pmax); alpha = __builtin_amdgcn_exp2f(m_reg - mn); m_reg = mn; }
; #pragma unroll
;     for (int r = 0; r < 16; ++r) p0[r] = p0[r] - mn;
; #pragma unroll
;     for (int r = 0; r < 16; ++r) p1[r] = p1[r] - mn;
; #pragma unroll
;     for (int r = 0; r < 16; ++r) p0[r] = __builtin_amdgcn_exp2f(p0[r]);
; }
; __device__ __forceinline__ void finishSM(f32x16& p0, f32x16& p1, float alpha, float& l_reg, bf16x8& pa0, bf16x8& pa1, bf16x8& pa2, bf16x8& pa3) {
; #pragma unroll
;     for (int r = 0; r < 16; ++r) p1[r] = __builtin_amdgcn_exp2f(p1[r]);
;     float ps = 0;
; #pragma unroll
;     for (int r = 0; r < 16; ++r) ps += p0[r];
; #pragma unroll
;     for (int r = 0; r < 16; ++r) ps += p1[r];
;     { auto rr = __builtin_amdgcn_permlane32_swap(__float_as_uint(ps), __float_as_uint(ps), false, false);
;       ps = __uint_as_float(rr[0]) + __uint_as_float(rr[1]); }
;     l_reg = l_reg * alpha + ps;
;     ...
;     PK4(p0, 0, pa0); PK4(p0, 8, pa1); PK4(p1, 0, pa2); PK4(p1, 8, pa3);
;     ...
; }
; template <int KB>
; __device__ __forceinline__ void qkt(f32x16& p0, f32x16& p1, lptr K_lds, int r32, int hi, const bf16x8* qr) {
;     p0 = f32x16{}; p1 = f32x16{};
;     lptr kb[4];
; #pragma unroll
;     for (int dd = 0; dd < 4; ++dd) kb[dd] = K_lds + KB * SHM_K + KSWZ(r32, (dd * 16 + hi * 8) * 2);
; #pragma unroll
;     for (int d0 = 0; d0 < 8; ++d0) { lptr a = kb[d0 & 3] + (d0 >> 2) * 128;
;         bf16x8 b0 = *reinterpret_cast<const LAS bf16x8*>(a);
;         bf16x8 b1 = *reinterpret_cast<const LAS bf16x8*>(a + 32 * 256);
;         p0 = __builtin_amdgcn_mfma_f32_32x32x16_bf16(b0, qr[d0], p0, 0, 0, 0);
;         p1 = __builtin_amdgcn_mfma_f32_32x32x16_bf16(b1, qr[d0], p1, 0, 0, 0); }
; }
.LBB0_871:
	v_cndmask_b32_e64 v1, v1, v220, s[10:11]
	v_sub_f32_e32 v92, v98, v1
	v_sub_f32_e32 v93, v99, v1
	v_sub_f32_e32 v94, v100, v1
	v_sub_f32_e32 v95, v101, v1
	v_sub_f32_e32 v74, v74, v1
	v_sub_f32_e32 v75, v75, v1
	v_sub_f32_e32 v96, v102, v1
	v_sub_f32_e32 v97, v103, v1
	v_sub_f32_e32 v68, v68, v1
	v_sub_f32_e32 v69, v69, v1
	v_sub_f32_e32 v76, v76, v1
	v_sub_f32_e32 v77, v77, v1
	v_sub_f32_e32 v66, v66, v1
	v_sub_f32_e32 v67, v67, v1
	v_sub_f32_e32 v70, v70, v1
	v_sub_f32_e32 v71, v71, v1
	v_exp_f32_e32 v98, v92
	v_exp_f32_e32 v113, v93
	v_exp_f32_e32 v99, v94
	v_exp_f32_e32 v112, v95
	v_exp_f32_e32 v100, v74
	v_exp_f32_e32 v111, v75
	v_exp_f32_e32 v101, v96
	v_exp_f32_e32 v110, v97
	v_exp_f32_e32 v102, v68
	v_exp_f32_e32 v109, v69
	v_exp_f32_e32 v103, v76
	v_exp_f32_e32 v108, v77
	v_exp_f32_e32 v104, v66
	v_exp_f32_e32 v107, v67
	v_exp_f32_e32 v105, v70
	v_exp_f32_e32 v106, v71
	v_sub_f32_e32 v220, v82, v1
	v_sub_f32_e32 v236, v83, v1
	v_sub_f32_e32 v237, v84, v1
	v_sub_f32_e32 v238, v85, v1
	v_sub_f32_e32 v239, v86, v1
	v_sub_f32_e32 v240, v87, v1
	v_sub_f32_e32 v241, v88, v1
	v_sub_f32_e32 v242, v89, v1
	v_sub_f32_e32 v243, v78, v1
	v_sub_f32_e32 v244, v79, v1
	v_sub_f32_e32 v245, v90, v1
	v_sub_f32_e32 v246, v91, v1
	v_sub_f32_e32 v247, v72, v1
	v_sub_f32_e32 v248, v73, v1
	v_sub_f32_e32 v249, v80, v1
	v_sub_f32_e32 v250, v81, v1
	s_waitcnt lgkmcnt(0)
	s_barrier
	ds_read_b128 v[66:69], v187 offset:32768
	ds_read_b128 v[70:73], v187 offset:40960
	ds_read_b128 v[146:149], v185 offset:32768
	ds_read_b128 v[150:153], v185 offset:40960
	s_waitcnt lgkmcnt(3)
	v_mfma_f32_32x32x16_bf16 v[82:97], v[66:69], v[142:145], 0
	v_exp_f32_e32 v220, v220
	v_add_f32_e32 v228, 0, v98
	v_add_f32_e32 v228, v113, v228
	v_add_f32_e32 v228, v99, v228
	v_add_f32_e32 v228, v112, v228
	v_add_f32_e32 v228, v100, v228
	v_add_f32_e32 v228, v111, v228
	s_waitcnt lgkmcnt(2)
	v_mfma_f32_32x32x16_bf16 v[66:81], v[70:73], v[142:145], 0
	v_add_f32_e32 v228, v101, v228
	v_add_f32_e32 v228, v110, v228
	v_add_f32_e32 v228, v102, v228
	v_add_f32_e32 v228, v109, v228
	v_add_f32_e32 v228, v103, v228
	v_add_f32_e32 v228, v108, v228
	v_add_f32_e32 v228, v104, v228
	s_waitcnt lgkmcnt(1)
	v_mfma_f32_32x32x16_bf16 v[82:97], v[146:149], v[138:141], v[82:97]
	v_exp_f32_e32 v230, v236
	v_add_f32_e32 v228, v107, v228
	v_exp_f32_e32 v231, v237
	v_add_f32_e32 v228, v105, v228
	v_exp_f32_e32 v232, v238
	s_waitcnt lgkmcnt(0)
	v_mfma_f32_32x32x16_bf16 v[66:81], v[150:153], v[138:141], v[66:81]
	v_add_f32_e32 v228, v106, v228
	v_exp_f32_e32 v233, v239
	v_add_f32_e32 v228, v220, v228
	v_exp_f32_e32 v234, v240
	v_add_f32_e32 v228, v230, v228
	ds_read_b128 v[146:149], v184 offset:32768
	ds_read_b128 v[150:153], v184 offset:40960
	s_waitcnt lgkmcnt(1)
	v_mfma_f32_32x32x16_bf16 v[82:97], v[146:149], v[134:137], v[82:97]
	v_exp_f32_e32 v235, v241
	v_add_f32_e32 v228, v231, v228
	v_exp_f32_e32 v236, v242
	v_add_f32_e32 v228, v232, v228
	v_exp_f32_e32 v237, v243
	s_waitcnt lgkmcnt(0)
	v_mfma_f32_32x32x16_bf16 v[66:81], v[150:153], v[134:137], v[66:81]
	v_add_f32_e32 v228, v233, v228
	v_exp_f32_e32 v238, v244
	v_add_f32_e32 v228, v234, v228
	v_exp_f32_e32 v239, v245
	v_add_f32_e32 v228, v235, v228
	ds_read_b128 v[146:149], v183 offset:32768
	ds_read_b128 v[150:153], v183 offset:40960
	s_waitcnt lgkmcnt(1)
	v_mfma_f32_32x32x16_bf16 v[82:97], v[146:149], v[130:133], v[82:97]
	v_exp_f32_e32 v240, v246
	v_add_f32_e32 v228, v236, v228
	v_exp_f32_e32 v241, v247
	v_add_f32_e32 v228, v237, v228
	v_exp_f32_e32 v242, v248
	s_waitcnt lgkmcnt(0)
	v_mfma_f32_32x32x16_bf16 v[66:81], v[150:153], v[130:133], v[66:81]
	v_add_f32_e32 v228, v238, v228
	v_exp_f32_e32 v243, v249
	v_add_f32_e32 v228, v239, v228
	v_exp_f32_e32 v244, v250
	v_add_f32_e32 v228, v240, v228
	v_add_f32_e32 v228, v241, v228
	ds_read_b128 v[146:149], v187 offset:32896
	ds_read_b128 v[150:153], v187 offset:41088
	s_waitcnt lgkmcnt(1)
	v_mfma_f32_32x32x16_bf16 v[82:97], v[146:149], v[126:129], v[82:97]
	v_add_f32_e32 v228, v242, v228
	v_add_f32_e32 v228, v243, v228
	v_add_f32_e32 v228, v244, v228
	v_mov_b32_e32 v229, v228
	v_cvt_pk_bf16_f32 v98, v98, v113
	v_cvt_pk_bf16_f32 v99, v99, v112
	v_cvt_pk_bf16_f32 v100, v100, v111
	v_cvt_pk_bf16_f32 v101, v101, v110
	s_waitcnt lgkmcnt(0)
	v_mfma_f32_32x32x16_bf16 v[66:81], v[150:153], v[126:129], v[66:81]
	v_cvt_pk_bf16_f32 v102, v102, v109
	v_cvt_pk_bf16_f32 v103, v103, v108
	v_cvt_pk_bf16_f32 v104, v104, v107
	v_cvt_pk_bf16_f32 v105, v105, v106
	v_cvt_pk_bf16_f32 v106, v220, v230
	v_cvt_pk_bf16_f32 v107, v231, v232
	v_cvt_pk_bf16_f32 v108, v233, v234
	v_cvt_pk_bf16_f32 v109, v235, v236
	ds_read_b128 v[146:149], v185 offset:32896
	ds_read_b128 v[150:153], v185 offset:41088
	s_waitcnt lgkmcnt(1)
	v_mfma_f32_32x32x16_bf16 v[82:97], v[146:149], v[122:125], v[82:97]
	v_cvt_pk_bf16_f32 v110, v237, v238
	v_cvt_pk_bf16_f32 v111, v239, v240
	v_cvt_pk_bf16_f32 v112, v241, v242
	v_cvt_pk_bf16_f32 v113, v243, v244
	s_nop 1
	v_permlane32_swap_b32_e32 v228, v229
	v_permlane32_swap_b32_e32 v98, v100
	v_permlane32_swap_b32_e32 v99, v101
	s_waitcnt lgkmcnt(0)
	v_mfma_f32_32x32x16_bf16 v[66:81], v[150:153], v[122:125], v[66:81]
	v_permlane32_swap_b32_e32 v102, v104
	v_permlane32_swap_b32_e32 v103, v105
	v_permlane32_swap_b32_e32 v106, v108
	v_permlane32_swap_b32_e32 v107, v109
	v_permlane32_swap_b32_e32 v110, v112
	v_permlane32_swap_b32_e32 v111, v113
	ds_read_b128 v[146:149], v184 offset:32896
	ds_read_b128 v[150:153], v184 offset:41088
	s_waitcnt lgkmcnt(1)
	v_mfma_f32_32x32x16_bf16 v[82:97], v[146:149], v[118:121], v[82:97]
	s_waitcnt lgkmcnt(0)
	v_mfma_f32_32x32x16_bf16 v[66:81], v[150:153], v[118:121], v[66:81]
	ds_read_b128 v[146:149], v183 offset:32896
	ds_read_b128 v[150:153], v183 offset:41088
	s_waitcnt lgkmcnt(1)
	v_mfma_f32_32x32x16_bf16 v[82:97], v[146:149], v[114:117], v[82:97]
	s_waitcnt lgkmcnt(0)
	v_mfma_f32_32x32x16_bf16 v[66:81], v[150:153], v[114:117], v[66:81]
	s_add_i32 s10, s88, 1
	s_cmp_lt_i32 s10, s81
	s_cselect_b64 s[40:41], -1, 0
	s_cmp_ge_i32 s10, s81
	s_cbranch_scc1 .LBB0_873
	v_add_u32_e32 v146, 0x41, v227
	v_add_u32_e32 v148, 0x61, v227
	v_ashrrev_i32_e32 v147, 31, v146
	v_ashrrev_i32_e32 v149, 31, v148
	v_lshlrev_b64 v[154:155], 8, v[146:147]
	v_lshlrev_b64 v[156:157], 8, v[148:149]
	v_lshl_add_u64 v[146:147], v[176:177], 0, v[154:155]
	v_lshl_add_u64 v[150:151], v[176:177], 0, v[156:157]
	v_lshl_add_u64 v[154:155], v[178:179], 0, v[154:155]
	v_lshl_add_u64 v[158:159], v[178:179], 0, v[156:157]
	global_load_dwordx4 v[146:149], v[146:147], off
	s_nop 0
	global_load_dwordx4 v[150:153], v[150:151], off
	s_nop 0
	global_load_dwordx4 v[154:157], v[154:155], off
	s_nop 0
	global_load_dwordx4 v[158:161], v[158:159], off
